# attention hot loop: back edge rotated out of the compute segment head (loop-back barrier is the loop head; exit path has its own barrier copy)
# speedup vs baseline: 1.0030x; 1.0030x over previous
.LBB0_713:
	v_mov_b32_e32 v19, v189
	v_lshl_add_u64 v[20:21], v[20:21], 0, v[18:19]
	s_movk_i32 s2, 0x2000
	v_add_co_u32_e32 v24, vcc, s2, v20
	v_add_u32_e32 v28, 64, v146
	v_add_u32_e32 v30, 0x60, v146
	v_addc_co_u32_e32 v25, vcc, 0, v21, vcc
	v_ashrrev_i32_e32 v29, 31, v28
	v_ashrrev_i32_e32 v31, 31, v30
	v_lshlrev_b64 v[28:29], v172, v[28:29]
	v_lshlrev_b64 v[30:31], v172, v[30:31]
	v_add_co_u32_e32 v20, vcc, s78, v20
	v_lshl_add_u64 v[28:29], v[28:29], 1, v[144:145]
	v_lshl_add_u64 v[64:65], v[30:31], 1, v[144:145]
	v_addc_co_u32_e32 v21, vcc, 0, v21, vcc
	global_load_dwordx4 v[24:27], v[24:25], off
	s_nop 0
	global_load_dwordx4 v[28:31], v[28:29], off
	s_nop 0
	global_load_dwordx4 v[64:67], v[64:65], off
	v_add_u32_e32 v156, 0xa0, v146
	global_load_dwordx4 v[120:123], v[20:21], off
	v_add_u32_e32 v20, 0x80, v146
	v_ashrrev_i32_e32 v21, 31, v20
	v_lshlrev_b64 v[20:21], v172, v[20:21]
	v_ashrrev_i32_e32 v157, 31, v156
	v_lshl_add_u64 v[20:21], v[20:21], 1, v[144:145]
	v_lshlrev_b64 v[68:69], v172, v[156:157]
	v_lshl_add_u64 v[68:69], v[68:69], 1, v[144:145]
	global_load_dwordx4 v[124:127], v[20:21], off
	global_load_dwordx4 v[128:131], v[68:69], off
	v_and_b32_e32 v151, 63, v22
	v_exp_f32_e32 v185, v1
	v_lshlrev_b32_e32 v1, 4, v151
	s_cmp_lg_u32 0, -1
	v_exp_f32_e32 v183, v0
	v_exp_f32_e32 v182, v2
	v_exp_f32_e32 v184, v3
	v_exp_f32_e32 v141, v4
	v_exp_f32_e32 v143, v5
	v_exp_f32_e32 v140, v6
	v_exp_f32_e32 v142, v7
	v_exp_f32_e32 v137, v8
	v_exp_f32_e32 v139, v9
	v_exp_f32_e32 v135, v10
	v_exp_f32_e32 v138, v11
	v_exp_f32_e32 v133, v12
	v_exp_f32_e32 v136, v13
	v_exp_f32_e32 v132, v14
	v_exp_f32_e32 v134, v15
	v_lshlrev_b32_e32 v0, 3, v151
	v_lshlrev_b32_e32 v2, 1, v151
	v_and_b32_e32 v1, 0xc0, v1
	v_and_b32_e32 v20, 0x3fffffc0, v22
	s_cselect_b32 s3, 0, 0
	s_lshl_b32 s57, s92, 2
	v_and_b32_e32 v2, 32, v2
	v_and_b32_e32 v3, 0x100, v0
	v_and_or_b32 v0, v0, 24, v1
	s_waitcnt vmcnt(3)
	v_lshl_add_u32 v163, v20, 2, 0
	s_add_i32 s20, s57, 4
	v_or3_b32 v165, v0, v2, v3
	s_mov_b32 s2, 1
	v_lshl_add_u64 v[152:153], s[46:47], 0, v[18:19]
	v_cmp_gt_u32_e64 s[40:41], 32, v151
	v_lshl_add_u32 v164, v149, 2, v163
	s_cmp_eq_u32 s92, 0
	v_add_u32_e32 v175, s3, v165
	v_and_b32_e32 v161, 7, v22
	s_waitcnt vmcnt(5)
	ds_write_b128 v176, v[24:27] offset:8192
	s_waitcnt vmcnt(4)
	ds_write_b128 v173, v[28:31] offset:32768
	s_waitcnt vmcnt(3)
	ds_write_b128 v174, v[64:67] offset:32768
	s_waitcnt lgkmcnt(0)
	s_barrier
	s_cbranch_scc1 .LBB0_730
	s_or_b32 s58, s57, 3
	s_cmp_lg_u32 0, -1
	s_cselect_b32 s2, 0, 0
	v_lshlrev_b32_e32 v0, 4, v161
	v_mov_b32_e32 v1, v189
	s_addk_i32 s2, 0x2000
	v_lshl_add_u64 v[0:1], v[16:17], 0, v[0:1]
	v_mov_b32_e32 v16, v189
	v_mov_b32_e32 v17, v189
	v_add_u32_e32 v157, s2, v165
	s_mov_b64 s[2:3], 0xe0
	v_lshl_add_u64 v[158:159], s[50:51], 0, v[0:1]
	v_mov_b32_e32 v18, v189
	v_mov_b32_e32 v19, v189
	v_mov_b32_e32 v20, v189
	v_mov_b32_e32 v21, v189
	v_mov_b32_e32 v22, v189
	v_mov_b32_e32 v23, v189
	v_mov_b32_e32 v24, v189
	v_mov_b32_e32 v25, v189
	v_mov_b32_e32 v26, v189
	v_mov_b32_e32 v27, v189
	v_mov_b32_e32 v28, v189
	v_mov_b32_e32 v29, v189
	v_mov_b32_e32 v30, v189
	v_mov_b32_e32 v31, v189
	v_mov_b64_e32 v[0:1], v[16:17]
	v_lshl_add_u64 v[154:155], v[146:147], 0, s[2:3]
	v_mov_b32_e32 v147, 0
	s_mov_b32 s59, 6
	v_mov_b64_e32 v[2:3], v[18:19]
	v_mov_b64_e32 v[4:5], v[20:21]
	v_mov_b64_e32 v[6:7], v[22:23]
	v_mov_b64_e32 v[8:9], v[24:25]
	v_mov_b64_e32 v[10:11], v[26:27]
	v_mov_b64_e32 v[12:13], v[28:29]
	v_mov_b64_e32 v[14:15], v[30:31]
	s_branch .LBB0_715
.Lmy_head715:
	s_barrier

.Lmy_exit715:
	s_barrier
	s_branch .LBB0_729
